# conv epilogue: ds_bpermute butterfly all-reduces replaced by DPP (quad_perm, row_half_mirror, row_mirror) + readlane reductions
# baseline (speedup 1.0000x reference)
; __device__ void conv_phase(LAS unsigned char* lds, const Params& p) {
;     ...
;         for (int lr = 0; lr < 2; ++lr)
; #pragma unroll
;             for (int lc = 0; lc < 2; ++lc) {
;                 const size_t token = (size_t)b * 4096 + (r0 + lr) * 64 + (c0 + lc);
;                 float v[8]; float s1 = 0.f, s2 = 0.f;
; #pragma unroll
;                 for (int c = 0; c < 8; ++c) { v[c] = (half ? acc[lc * 2 + lr][c] : acc[lr * 2 + lc][c]) + cbv[c]; s1 += v[c]; s2 += v[c] * v[c]; }
; #pragma unroll
;                 for (int m = 32; m >= 1; m >>= 1) { s1 += __shfl_xor(s1, m); s2 += __shfl_xor(s2, m); }
.LBB0_371:
	global_load_dwordx4 v[22:25], v[76:77], off
	global_load_dwordx4 v[14:17], v[76:77], off offset:16
	v_ashrrev_i32_e32 v115, 31, v114
	v_lshlrev_b64 v[36:37], 12, v[114:115]
	v_lshl_or_b32 v48, v124, 6, v36
	v_or_b32_e32 v36, v48, v123
	v_lshlrev_b64 v[40:41], 10, v[36:37]
	v_lshl_add_u64 v[38:39], v[70:71], 0, v[40:41]
	global_load_dwordx4 v[50:53], v[38:39], off
	global_load_dwordx4 v[18:21], v[78:79], off offset:16
	global_load_dwordx4 v[30:33], v[78:79], off
	global_load_dwordx4 v[10:13], v[80:81], off offset:16
	global_load_dwordx4 v[26:29], v[80:81], off
	global_load_dwordx4 v[2:5], v[82:83], off offset:16
	global_load_dwordx4 v[6:9], v[82:83], off
	v_add_co_u32_e32 v252, vcc, 0x10000, v40
	s_nop 1
	v_addc_co_u32_e32 v253, vcc, 0, v41, vcc
	v_lshl_add_u64 v[254:255], s[68:69], 0, v[66:67]
	v_add_co_u32_e32 v254, vcc, s35, v254
	s_nop 1
	v_addc_co_u32_e32 v255, vcc, 0, v255, vcc
	v_lshl_add_u64 v[192:193], v[254:255], 0, v[40:41]
	v_lshl_add_u64 v[196:197], v[72:73], 0, v[40:41]
	v_lshl_add_u64 v[200:201], v[74:75], 0, v[40:41]
	v_lshl_add_u64 v[204:205], v[70:71], 0, v[40:41]
	v_lshl_add_u64 v[208:209], v[254:255], 0, v[40:41]
	v_lshl_add_u64 v[212:213], v[72:73], 0, v[40:41]
	v_lshl_add_u64 v[216:217], v[74:75], 0, v[40:41]
	v_lshl_add_u64 v[220:221], v[70:71], 0, v[252:253]
	v_lshl_add_u64 v[224:225], v[254:255], 0, v[252:253]
	v_lshl_add_u64 v[228:229], v[72:73], 0, v[252:253]
	v_lshl_add_u64 v[232:233], v[74:75], 0, v[252:253]
	v_lshl_add_u64 v[236:237], v[70:71], 0, v[252:253]
	v_lshl_add_u64 v[240:241], v[254:255], 0, v[252:253]
	v_lshl_add_u64 v[244:245], v[72:73], 0, v[252:253]
	v_lshl_add_u64 v[248:249], v[74:75], 0, v[252:253]
	global_load_dwordx4 v[192:195], v[192:193], off
	global_load_dwordx4 v[196:199], v[196:197], off
	global_load_dwordx4 v[200:203], v[200:201], off
	global_load_dwordx4 v[204:207], v[204:205], off offset:1024
	global_load_dwordx4 v[208:211], v[208:209], off offset:1024
	global_load_dwordx4 v[212:215], v[212:213], off offset:1024
	global_load_dwordx4 v[216:219], v[216:217], off offset:1024
	global_load_dwordx4 v[220:223], v[220:221], off
	global_load_dwordx4 v[224:227], v[224:225], off
	global_load_dwordx4 v[228:231], v[228:229], off
	global_load_dwordx4 v[232:235], v[232:233], off
	global_load_dwordx4 v[236:239], v[236:237], off offset:1024
	global_load_dwordx4 v[240:243], v[240:241], off offset:1024
	global_load_dwordx4 v[244:247], v[244:245], off offset:1024
	global_load_dwordx4 v[248:251], v[248:249], off offset:1024
	v_and_b32_e32 v38, 64, v69
	v_xor_b32_e32 v39, 32, v69
	v_add_u32_e32 v116, 64, v38
	v_cmp_lt_i32_e32 vcc, v39, v116
	v_xor_b32_e32 v65, 4, v69
	v_mov_b32_e32 v42, v88
	v_cndmask_b32_e32 v38, v69, v39, vcc
	v_lshlrev_b32_e32 v46, 2, v38
	v_xor_b32_e32 v47, 16, v69
	v_cmp_lt_i32_e32 vcc, v47, v116
	v_xor_b32_e32 v49, 8, v69
	s_waitcnt vmcnt(23)
	v_pk_add_f32 v[54:55], v[92:93], v[22:23]
	s_waitcnt vmcnt(22)
	v_pk_mov_b32 v[38:39], v[16:17], v[16:17] op_sel:[1,0]
	v_mul_f32_e32 v44, v55, v55
	v_add_f32_e32 v39, 0, v54
	v_pk_add_f32 v[56:57], v[90:91], v[24:25]
	v_add_f32_e32 v39, v55, v39
	v_pk_fma_f32 v[44:45], v[54:55], v[54:55], v[44:45] op_sel_hi:[1,1,0]
	v_mul_f32_e32 v62, v57, v57
	v_add_f32_e32 v39, v56, v39
	v_pk_fma_f32 v[44:45], v[56:57], v[56:57], v[44:45]
	v_pk_add_f32 v[58:59], v[86:87], v[14:15]
	v_add_f32_e32 v39, v57, v39
	v_pk_add_f32 v[44:45], v[62:63], v[44:45] op_sel_hi:[0,1]
	v_pk_add_f32 v[60:61], v[88:89], v[16:17] op_sel:[0,1] op_sel_hi:[1,0]
	v_mul_f32_e32 v64, v59, v59
	v_mov_b32_e32 v43, v59
	v_add_f32_e32 v39, v58, v39
	v_pk_fma_f32 v[44:45], v[58:59], v[58:59], v[44:45]
	v_pk_mul_f32 v[114:115], v[60:61], v[60:61]
	v_pk_add_f32 v[44:45], v[64:65], v[44:45] op_sel_hi:[0,1]
	v_pk_add_f32 v[42:43], v[42:43], v[38:39]
	v_pk_mov_b32 v[114:115], v[114:115], v[88:89] op_sel:[1,0]
	v_mov_b32_e32 v45, v17
	v_pk_mul_f32 v[62:63], v[60:61], v[42:43]
	v_pk_add_f32 v[42:43], v[60:61], v[42:43]
	v_pk_add_f32 v[44:45], v[114:115], v[44:45]
	v_mov_b32_e32 v63, v43
	v_pk_add_f32 v[42:43], v[62:63], v[44:45]
	s_nop 1
	v_add_f32_dpp v252, v42, v42 quad_perm:[1,0,3,2] row_mask:0xf bank_mask:0xf
	v_add_f32_dpp v253, v43, v43 quad_perm:[1,0,3,2] row_mask:0xf bank_mask:0xf
	s_nop 0
	v_add_f32_dpp v252, v252, v252 quad_perm:[2,3,0,1] row_mask:0xf bank_mask:0xf
	v_add_f32_dpp v253, v253, v253 quad_perm:[2,3,0,1] row_mask:0xf bank_mask:0xf
	s_nop 0
	v_add_f32_dpp v252, v252, v252 row_half_mirror row_mask:0xf bank_mask:0xf
	v_add_f32_dpp v253, v253, v253 row_half_mirror row_mask:0xf bank_mask:0xf
	s_nop 0
	v_add_f32_dpp v252, v252, v252 row_mirror row_mask:0xf bank_mask:0xf
	v_add_f32_dpp v253, v253, v253 row_mirror row_mask:0xf bank_mask:0xf
	s_nop 0
	v_readlane_b32 s76, v252, 0
	v_readlane_b32 s77, v252, 16
	v_readlane_b32 s78, v252, 32
	v_readlane_b32 s79, v252, 48
	v_readlane_b32 s80, v253, 0
	v_readlane_b32 s81, v253, 16
	v_readlane_b32 s82, v253, 32
	v_readlane_b32 s83, v253, 48
	v_mov_b32_e32 v252, s76
	v_add_f32_e32 v252, s77, v252
	v_add_f32_e32 v252, s78, v252
	v_add_f32_e32 v252, s79, v252
	v_mov_b32_e32 v253, s80
	v_add_f32_e32 v253, s81, v253
	v_add_f32_e32 v253, s82, v253
	v_add_f32_e32 v253, s83, v253
	v_cndmask_b32_e32 v47, v69, v47, vcc
	v_lshlrev_b32_e32 v47, 2, v47
	v_cmp_lt_i32_e32 vcc, v49, v116
	v_xor_b32_e32 v39, 2, v69
	v_cndmask_b32_e32 v42, v69, v49, vcc
	v_lshlrev_b32_e32 v42, 2, v42
	v_cmp_lt_i32_e32 vcc, v65, v116
	v_xor_b32_e32 v114, 1, v69
	v_cndmask_b32_e32 v43, v69, v65, vcc
	v_lshlrev_b32_e32 v43, 2, v43
	v_cmp_lt_i32_e32 vcc, v39, v116
	s_waitcnt vmcnt(21)
; __device__ __forceinline__ unsigned cvt_pk_bf16(float lo, float hi) { unsigned r; asm volatile("v_cvt_pk_bf16_f32 %0, %1, %2" : "=v"(r) : "v"(lo), "v"(hi)); return r; }
; __device__ __forceinline__ float bf_lo(unsigned u) { return __uint_as_float(u << 16); }
; __device__ __forceinline__ float bf_hi(unsigned u) { return __uint_as_float(u & 0xffff0000u); }
; __device__ __forceinline__ float siluf_(float v) { return v * __builtin_amdgcn_rcpf(1.f + __expf(-v)); }
; __device__ void conv_phase(LAS unsigned char* lds, const Params& p) {
;     ...
;                 for (int m = 32; m >= 1; m >>= 1) { s1 += __shfl_xor(s1, m); s2 += __shfl_xor(s2, m); }
;                 const float mean = s1 * (1.f / 512.f), var = fmaxf(s2 * (1.f / 512.f) - mean * mean, 0.f), rstd = rsqrtf(var + EPS);
;                 const u32x4 gbr = *(const u32x4*)(GBp + token * 512 + ch0);
;                 const float gbv[8] = {bf_lo(gbr[0]), bf_hi(gbr[0]), bf_lo(gbr[1]), bf_hi(gbr[1]), bf_lo(gbr[2]), bf_hi(gbr[2]), bf_lo(gbr[3]), bf_hi(gbr[3])};
;                 float y[8];
; #pragma unroll
;                 for (int c = 0; c < 8; ++c) { const float t = (v[c] - mean) * rstd * lg[c] + lbv[c]; y[c] = siluf_(t) * gbv[c]; }
;                 u32x4 ob = {cvt_pk_bf16(y[0], y[1]), cvt_pk_bf16(y[2], y[3]), cvt_pk_bf16(y[4], y[5]), cvt_pk_bf16(y[6], y[7])};
;                 *(u32x4*)(A2 + token * 1024 + 512 + ch0) = ob;
;                 const u32x4 fo = *(const u32x4*)(O + token * 512 + ch0), bo = *(const u32x4*)(O + ((size_t)NLAT + token) * 512 + ch0);
;                 float ov[8]; float ss = 0.f;
; #pragma unroll
;                 for (int c = 0; c < 4; ++c) { ov[2 * c] = bf_lo(fo[c]) + bf_lo(bo[c]); ov[2 * c + 1] = bf_hi(fo[c]) + bf_hi(bo[c]); }
; #pragma unroll
;                 for (int c = 0; c < 8; ++c) ss += ov[c] * ov[c];
;                 ss += __shfl_xor(ss, 1); ss += __shfl_xor(ss, 2); ss += __shfl_xor(ss, 4); ss += __shfl_xor(ss, 8);
;                 const float rn = rsqrtf(ss * (1.f / 128.f) + EPS);
	v_and_b32_e32 v49, 0xffff0000, v50
	v_cndmask_b32_e32 v39, v69, v39, vcc
	v_lshlrev_b32_e32 v44, 2, v39
	v_cmp_lt_i32_e32 vcc, v114, v116
	v_lshlrev_b32_e32 v39, 16, v50
	v_cndmask_b32_e32 v45, v69, v114, vcc
	v_lshlrev_b32_e32 v45, 2, v45
	v_lshlrev_b32_e32 v114, 16, v51
	v_and_b32_e32 v115, 0xffff0000, v51
	v_lshlrev_b32_e32 v64, 16, v52
	v_and_b32_e32 v52, 0xffff0000, v52
	v_lshlrev_b32_e32 v65, 16, v53
	v_and_b32_e32 v53, 0xffff0000, v53
	v_mov_b32_e32 v50, v252
	v_mov_b32_e32 v51, v253
	s_nop 0
	v_pk_mul_f32 v[50:51], v[50:51], s[34:35] op_sel_hi:[1,0]
	s_nop 0
	v_fma_f32 v50, -v51, v51, v50
	v_max_f32_e32 v50, 0, v50
	v_add_f32_e32 v50, 0x358637bd, v50
	v_mul_f32_e32 v62, 0x4b800000, v50
	v_cmp_gt_f32_e32 vcc, s3, v50
	v_sub_f32_e32 v55, v55, v51
	v_sub_f32_e32 v54, v54, v51
	v_cndmask_b32_e32 v50, v50, v62, vcc
	v_rsq_f32_e32 v50, v50
	v_sub_f32_e32 v56, v56, v51
	v_sub_f32_e32 v57, v57, v51
	v_sub_f32_e32 v58, v58, v51
	v_mul_f32_e32 v62, 0x45800000, v50
	v_cndmask_b32_e32 v50, v50, v62, vcc
	v_mul_f32_e32 v55, v55, v50
	v_mul_f32_e32 v54, v54, v50
	v_mul_f32_e32 v56, v56, v50
	v_mul_f32_e32 v57, v57, v50
	s_waitcnt vmcnt(17)
	v_fma_f32 v55, v31, v55, v27
	v_mul_f32_e32 v58, v58, v50
	v_fma_f32 v54, v30, v54, v26
	v_fma_f32 v56, v32, v56, v28
	v_fma_f32 v57, v33, v57, v29
	v_mul_f32_e32 v63, 0xbfb8aa3b, v55
	v_fma_f32 v58, v18, v58, v10
	v_mul_f32_e32 v62, 0xbfb8aa3b, v54
	v_mul_f32_e32 v116, 0xbfb8aa3b, v56
	v_mul_f32_e32 v117, 0xbfb8aa3b, v57
	v_exp_f32_e32 v63, v63
	v_mul_f32_e32 v124, 0xbfb8aa3b, v58
	v_exp_f32_e32 v62, v62
	v_exp_f32_e32 v116, v116
	v_exp_f32_e32 v117, v117
	v_exp_f32_e32 v124, v124
	v_add_f32_e32 v63, 1.0, v63
	v_add_f32_e32 v62, 1.0, v62
	v_add_f32_e32 v116, 1.0, v116
	v_add_f32_e32 v117, 1.0, v117
	v_rcp_f32_e32 v63, v63
	v_sub_f32_e32 v59, v59, v51
	v_add_f32_e32 v124, 1.0, v124
	v_rcp_f32_e32 v62, v62
	v_rcp_f32_e32 v116, v116
	v_rcp_f32_e32 v117, v117
	v_mul_f32_e32 v59, v59, v50
	v_rcp_f32_e32 v124, v124
	v_fma_f32 v59, v19, v59, v11
	v_mul_f32_e32 v125, 0xbfb8aa3b, v59
	v_mul_f32_e32 v55, v55, v63
	v_mul_f32_e32 v54, v54, v62
	v_mul_f32_e32 v56, v56, v116
	v_mul_f32_e32 v57, v57, v117
	v_mul_f32_e32 v49, v55, v49
	v_exp_f32_e32 v55, v125
	v_mul_f32_e32 v39, v54, v39
	v_mul_f32_e32 v54, v56, v114
	v_mul_f32_e32 v56, v57, v115
	v_mul_f32_e32 v57, v58, v124
	v_sub_f32_e32 v58, v61, v51
	v_sub_f32_e32 v51, v60, v51
	v_mul_f32_e32 v58, v58, v50
	v_mul_f32_e32 v50, v51, v50
	v_fma_f32 v58, v20, v58, v12
	v_fma_f32 v50, v21, v50, v13
	v_add_f32_e32 v55, 1.0, v55
	v_mul_f32_e32 v61, 0xbfb8aa3b, v58
	v_mul_f32_e32 v51, 0xbfb8aa3b, v50
	v_rcp_f32_e32 v55, v55
	v_exp_f32_e32 v61, v61
	v_exp_f32_e32 v51, v51
	v_mul_f32_e32 v57, v57, v64
	v_mul_f32_e32 v55, v59, v55
	v_add_f32_e32 v59, 1.0, v61
	v_add_f32_e32 v51, 1.0, v51
	v_rcp_f32_e32 v59, v59
	v_rcp_f32_e32 v51, v51
	v_mul_f32_e32 v52, v55, v52
	v_mul_f32_e32 v55, v58, v59
	v_mul_f32_e32 v50, v50, v51
	v_mul_f32_e32 v55, v55, v65
	v_mul_f32_e32 v53, v50, v53
	v_cvt_pk_bf16_f32 v50, v39, v49
	v_cvt_pk_bf16_f32 v51, v54, v56
	v_cvt_pk_bf16_f32 v52, v57, v52
	v_cvt_pk_bf16_f32 v53, v55, v53
	v_lshlrev_b64 v[54:55], 11, v[36:37]
	v_lshl_add_u64 v[62:63], v[84:85], 0, v[54:55]
	global_store_dwordx4 v[62:63], v[50:53], off offset:1024
	v_lshl_add_u64 v[58:59], v[72:73], 0, v[40:41]
	s_nop 0
	v_lshl_add_u64 v[50:51], s[68:69], 0, v[40:41]
	v_lshl_add_u64 v[50:51], v[50:51], 0, v[66:67]
	v_add_co_u32_e32 v60, vcc, s35, v50
	v_lshl_add_u64 v[40:41], v[74:75], 0, v[40:41]
	s_nop 0
	v_addc_co_u32_e32 v61, vcc, 0, v51, vcc
	s_waitcnt vmcnt(14)
	v_mov_b32_e32 v50, v192
	v_mov_b32_e32 v51, v193
	v_mov_b32_e32 v52, v194
	v_mov_b32_e32 v53, v195
	v_mov_b32_e32 v54, v196
	v_mov_b32_e32 v55, v197
	v_mov_b32_e32 v56, v198
	v_mov_b32_e32 v57, v199
	v_lshlrev_b32_e32 v36, 16, v50
	s_waitcnt vmcnt(13)
	v_mov_b32_e32 v58, v200
	v_mov_b32_e32 v59, v201
	v_mov_b32_e32 v60, v202
	v_mov_b32_e32 v61, v203
	v_lshlrev_b32_e32 v39, 16, v54
	v_and_b32_e32 v49, 0xffff0000, v50
	v_and_b32_e32 v124, 0xffff0000, v54
	v_lshlrev_b32_e32 v41, 16, v51
	v_lshlrev_b32_e32 v65, 16, v55
	v_and_b32_e32 v40, 0xffff0000, v51
	v_and_b32_e32 v64, 0xffff0000, v55
	v_add_f32_e32 v36, v36, v39
	v_lshlrev_b32_e32 v51, 16, v52
	v_and_b32_e32 v50, 0xffff0000, v52
	v_lshlrev_b32_e32 v115, 16, v53
	v_and_b32_e32 v114, 0xffff0000, v53
	v_add_f32_e32 v39, v49, v124
	v_pk_add_f32 v[52:53], v[64:65], v[40:41]
	v_mul_f32_e32 v49, v36, v36
	v_lshlrev_b32_e32 v55, 16, v56
	v_and_b32_e32 v54, 0xffff0000, v56
	v_pk_mul_f32 v[40:41], v[52:53], v[52:53]
	v_fmac_f32_e32 v49, v39, v39
	v_pk_add_f32 v[50:51], v[54:55], v[50:51]
	v_add_f32_e32 v41, v41, v49
	v_lshlrev_b32_e32 v117, 16, v57
	v_and_b32_e32 v116, 0xffff0000, v57
	v_pk_mul_f32 v[56:57], v[50:51], v[50:51]
	v_add_f32_e32 v40, v40, v41
	v_pk_add_f32 v[54:55], v[116:117], v[114:115]
	v_add_f32_e32 v40, v57, v40
	v_pk_mul_f32 v[64:65], v[54:55], v[54:55]
	v_add_f32_e32 v40, v56, v40
	v_add_f32_e32 v40, v65, v40
	v_add_f32_e32 v40, v64, v40
	s_nop 1
	v_add_f32_dpp v252, v40, v40 quad_perm:[1,0,3,2] row_mask:0xf bank_mask:0xf
	s_nop 1
	v_add_f32_dpp v252, v252, v252 quad_perm:[2,3,0,1] row_mask:0xf bank_mask:0xf
	s_nop 1
	v_add_f32_dpp v252, v252, v252 row_half_mirror row_mask:0xf bank_mask:0xf
	s_nop 1
	v_add_f32_dpp v252, v252, v252 row_mirror row_mask:0xf bank_mask:0xf
	v_or_b32_e32 v49, 1, v123
	v_pk_mov_b32 v[40:41], v[112:113], v[112:113] op_sel:[1,0]
	v_mov_b32_e32 v56, v252
	v_fmamk_f32 v56, v56, 0x3c000000, v120
	v_mul_f32_e32 v57, 0x4b800000, v56
	v_cmp_gt_f32_e32 vcc, s3, v56
	v_lshlrev_b32_e32 v64, 16, v58
	v_cndmask_b32_e32 v56, v56, v57, vcc
	v_rsq_f32_e32 v56, v56
; __device__ __forceinline__ unsigned cvt_pk_bf16(float lo, float hi) { unsigned r; asm volatile("v_cvt_pk_bf16_f32 %0, %1, %2" : "=v"(r) : "v"(lo), "v"(hi)); return r; }
; __device__ __forceinline__ float bf_lo(unsigned u) { return __uint_as_float(u << 16); }
; __device__ __forceinline__ float bf_hi(unsigned u) { return __uint_as_float(u & 0xffff0000u); }
; __device__ void conv_phase(LAS unsigned char* lds, const Params& p) {
;     ...
;                 float v[8]; float s1 = 0.f, s2 = 0.f;
; #pragma unroll
;                 for (int c = 0; c < 8; ++c) { v[c] = (half ? acc[lc * 2 + lr][c] : acc[lr * 2 + lc][c]) + cbv[c]; s1 += v[c]; s2 += v[c] * v[c]; }
; #pragma unroll
;                 for (int m = 32; m >= 1; m >>= 1) { s1 += __shfl_xor(s1, m); s2 += __shfl_xor(s2, m); }
;                 const float mean = s1 * (1.f / 512.f), var = fmaxf(s2 * (1.f / 512.f) - mean * mean, 0.f), rstd = rsqrtf(var + EPS);
;     ...
;                 const u32x4 fo = *(const u32x4*)(O + token * 512 + ch0), bo = *(const u32x4*)(O + ((size_t)NLAT + token) * 512 + ch0);
;                 float ov[8]; float ss = 0.f;
; #pragma unroll
;                 for (int c = 0; c < 4; ++c) { ov[2 * c] = bf_lo(fo[c]) + bf_lo(bo[c]); ov[2 * c + 1] = bf_hi(fo[c]) + bf_hi(bo[c]); }
; #pragma unroll
;                 for (int c = 0; c < 8; ++c) ss += ov[c] * ov[c];
;                 ss += __shfl_xor(ss, 1); ss += __shfl_xor(ss, 2); ss += __shfl_xor(ss, 4); ss += __shfl_xor(ss, 8);
;                 const float rn = rsqrtf(ss * (1.f / 128.f) + EPS);
;                 const u32x4 gar = *(const u32x4*)(GAp + token * 512 + ch0);
;                 const float gav[8] = {bf_lo(gar[0]), bf_hi(gar[0]), bf_lo(gar[1]), bf_hi(gar[1]), bf_lo(gar[2]), bf_hi(gar[2]), bf_lo(gar[3]), bf_hi(gar[3])};
;                 float z[8];
; #pragma unroll
;                 for (int c = 0; c < 8; ++c) z[c] = ov[c] * rn * hg[c] * gav[c];
;                 u32x4 oa = {cvt_pk_bf16(z[0], z[1]), cvt_pk_bf16(z[2], z[3]), cvt_pk_bf16(z[4], z[5]), cvt_pk_bf16(z[6], z[7])};
;                 *(u32x4*)(A2 + token * 1024 + ch0) = oa;
;             }
	v_and_b32_e32 v58, 0xffff0000, v58
	v_lshlrev_b32_e32 v65, 16, v59
	v_and_b32_e32 v59, 0xffff0000, v59
	v_mul_f32_e32 v113, 0x45800000, v56
	v_cndmask_b32_e32 v56, v56, v113, vcc
	v_mul_f32_e32 v36, v36, v56
	v_mul_f32_e32 v39, v39, v56
	v_mul_f32_e32 v53, v53, v56
	v_mul_f32_e32 v52, v52, v56
	v_mul_f32_e32 v51, v51, v56
	v_mul_f32_e32 v50, v50, v56
	v_lshlrev_b32_e32 v112, 16, v60
	v_and_b32_e32 v57, 0xffff0000, v60
	v_mul_f32_e32 v55, v55, v56
	v_mul_f32_e32 v54, v54, v56
	v_mul_f32_e32 v36, v6, v36
	v_mul_f32_e32 v39, v7, v39
	v_mul_f32_e32 v53, v8, v53
	v_mul_f32_e32 v52, v9, v52
	v_mul_f32_e32 v51, v2, v51
	v_mul_f32_e32 v50, v3, v50
	v_lshlrev_b32_e32 v60, 16, v61
	v_and_b32_e32 v61, 0xffff0000, v61
	v_mul_f32_e32 v55, v4, v55
	v_mul_f32_e32 v54, v5, v54
	v_mul_f32_e32 v36, v36, v64
	v_mul_f32_e32 v39, v39, v58
	v_mul_f32_e32 v53, v53, v65
	v_mul_f32_e32 v52, v52, v59
	v_mul_f32_e32 v56, v51, v112
	v_mul_f32_e32 v57, v50, v57
	v_cvt_pk_bf16_f32 v50, v36, v39
	v_cvt_pk_bf16_f32 v51, v53, v52
	v_mul_f32_e32 v55, v55, v60
	v_mul_f32_e32 v54, v54, v61
	v_cvt_pk_bf16_f32 v52, v56, v57
	v_cvt_pk_bf16_f32 v53, v55, v54
	global_store_dwordx4 v[62:63], v[50:53], off
	v_cndmask_b32_e64 v61, v107, v95, s[6:7]
	v_cndmask_b32_e64 v60, v106, v94, s[6:7]
	v_cndmask_b32_e64 v51, v111, v99, s[6:7]
	v_cndmask_b32_e64 v50, v110, v98, s[6:7]
	v_pk_add_f32 v[54:55], v[50:51], v[22:23]
	v_cndmask_b32_e64 v53, v109, v97, s[6:7]
	v_add_f32_e32 v36, 0, v54
	v_cndmask_b32_e64 v52, v108, v96, s[6:7]
	v_add_f32_e32 v39, v55, v36
	v_mul_f32_e32 v36, v55, v55
	v_pk_add_f32 v[56:57], v[52:53], v[24:25]
	v_pk_fma_f32 v[50:51], v[54:55], v[54:55], v[36:37] op_sel_hi:[1,1,0]
	v_add_f32_e32 v36, v56, v39
	v_pk_fma_f32 v[50:51], v[56:57], v[56:57], v[50:51]
	v_add_f32_e32 v39, v57, v36
	v_mul_f32_e32 v36, v57, v57
	v_pk_add_f32 v[58:59], v[36:37], v[50:51] op_sel_hi:[0,1]
	v_or_b32_e32 v36, v48, v49
	v_lshlrev_b64 v[62:63], 10, v[36:37]
	v_lshl_add_u64 v[50:51], v[70:71], 0, v[62:63]
	s_waitcnt vmcnt(13)
	v_mov_b32_e32 v50, v204
	v_mov_b32_e32 v51, v205
	v_mov_b32_e32 v52, v206
	v_mov_b32_e32 v53, v207
	v_pk_add_f32 v[60:61], v[60:61], v[14:15]
	v_or_b32_e32 v48, 64, v48
	v_pk_fma_f32 v[58:59], v[60:61], v[60:61], v[58:59]
	v_mul_f32_e32 v64, v61, v61
	v_pk_add_f32 v[58:59], v[64:65], v[58:59] op_sel_hi:[0,1]
	v_cndmask_b32_e64 v65, v41, v122, s[6:7]
	v_cndmask_b32_e64 v64, v40, v121, s[6:7]
	v_pk_add_f32 v[112:113], v[64:65], v[16:17] op_sel:[0,1] op_sel_hi:[1,0]
	v_add_f32_e32 v39, v60, v39
	v_pk_mul_f32 v[114:115], v[112:113], v[112:113]
	v_mov_b32_e32 v116, v64
	v_mov_b32_e32 v117, v61
	v_pk_add_f32 v[116:117], v[116:117], v[38:39]
	v_pk_mov_b32 v[64:65], v[114:115], v[64:65] op_sel:[1,0]
	v_mov_b32_e32 v59, v17
	v_pk_add_f32 v[58:59], v[64:65], v[58:59]
	v_pk_mul_f32 v[64:65], v[112:113], v[116:117]
	v_pk_add_f32 v[114:115], v[112:113], v[116:117]
	v_cndmask_b32_e64 v41, v122, v41, s[6:7]
	v_mov_b32_e32 v65, v115
	v_pk_add_f32 v[58:59], v[64:65], v[58:59]
	s_nop 1
	v_add_f32_dpp v252, v58, v58 quad_perm:[1,0,3,2] row_mask:0xf bank_mask:0xf
	v_add_f32_dpp v253, v59, v59 quad_perm:[1,0,3,2] row_mask:0xf bank_mask:0xf
	s_nop 0
	v_add_f32_dpp v252, v252, v252 quad_perm:[2,3,0,1] row_mask:0xf bank_mask:0xf
	v_add_f32_dpp v253, v253, v253 quad_perm:[2,3,0,1] row_mask:0xf bank_mask:0xf
	s_nop 0
	v_add_f32_dpp v252, v252, v252 row_half_mirror row_mask:0xf bank_mask:0xf
	v_add_f32_dpp v253, v253, v253 row_half_mirror row_mask:0xf bank_mask:0xf
	s_nop 0
	v_add_f32_dpp v252, v252, v252 row_mirror row_mask:0xf bank_mask:0xf
	v_add_f32_dpp v253, v253, v253 row_mirror row_mask:0xf bank_mask:0xf
	s_nop 0
	v_readlane_b32 s76, v252, 0
	v_readlane_b32 s77, v252, 16
	v_readlane_b32 s78, v252, 32
	v_readlane_b32 s79, v252, 48
	v_readlane_b32 s80, v253, 0
	v_readlane_b32 s81, v253, 16
	v_readlane_b32 s82, v253, 32
	v_readlane_b32 s83, v253, 48
	v_mov_b32_e32 v252, s76
	v_add_f32_e32 v252, s77, v252
	v_add_f32_e32 v252, s78, v252
	v_add_f32_e32 v252, s79, v252
	v_mov_b32_e32 v253, s80
	v_add_f32_e32 v253, s81, v253
	v_add_f32_e32 v253, s82, v253
	v_add_f32_e32 v253, s83, v253
	v_cndmask_b32_e64 v40, v121, v40, s[6:7]
	v_mov_b32_e32 v58, v252
	v_mov_b32_e32 v59, v253
	s_nop 0
	v_pk_mul_f32 v[58:59], v[58:59], s[34:35] op_sel_hi:[1,0]
	v_lshlrev_b32_e32 v64, 16, v50
	v_fma_f32 v39, -v59, v59, v58
	v_max_f32_e32 v39, 0, v39
	v_add_f32_e32 v39, 0x358637bd, v39
	v_mul_f32_e32 v58, 0x4b800000, v39
	v_cmp_gt_f32_e32 vcc, s3, v39
	v_sub_f32_e32 v54, v54, v59
	v_sub_f32_e32 v55, v55, v59
	v_cndmask_b32_e32 v39, v39, v58, vcc
	v_rsq_f32_e32 v39, v39
	v_sub_f32_e32 v56, v56, v59
	v_sub_f32_e32 v57, v57, v59
	v_sub_f32_e32 v60, v60, v59
	v_mul_f32_e32 v58, 0x45800000, v39
	v_cndmask_b32_e32 v39, v39, v58, vcc
	v_mul_f32_e32 v54, v54, v39
	v_fma_f32 v54, v30, v54, v26
	v_mul_f32_e32 v58, 0xbfb8aa3b, v54
	v_exp_f32_e32 v58, v58
	v_mul_f32_e32 v55, v55, v39
	v_fma_f32 v55, v31, v55, v27
	v_mul_f32_e32 v115, 0xbfb8aa3b, v55
	v_add_f32_e32 v58, 1.0, v58
	v_exp_f32_e32 v115, v115
	v_rcp_f32_e32 v58, v58
	v_mul_f32_e32 v56, v56, v39
	v_mul_f32_e32 v57, v57, v39
	v_add_f32_e32 v115, 1.0, v115
	v_mul_f32_e32 v54, v54, v58
	v_fma_f32 v56, v32, v56, v28
	v_fma_f32 v57, v33, v57, v29
	v_rcp_f32_e32 v115, v115
	v_mul_f32_e32 v54, v54, v64
	v_mul_f32_e32 v58, 0xbfb8aa3b, v56
	v_mul_f32_e32 v64, 0xbfb8aa3b, v57
	v_exp_f32_e32 v58, v58
	v_exp_f32_e32 v64, v64
	v_mul_f32_e32 v60, v60, v39
	v_and_b32_e32 v50, 0xffff0000, v50
	v_mul_f32_e32 v55, v55, v115
	v_fma_f32 v60, v18, v60, v10
	v_mul_f32_e32 v50, v55, v50
	v_add_f32_e32 v55, 1.0, v58
	v_add_f32_e32 v58, 1.0, v64
	v_mul_f32_e32 v64, 0xbfb8aa3b, v60
; __device__ __forceinline__ float bf_lo(unsigned u) { return __uint_as_float(u << 16); }
; __device__ void conv_phase(LAS unsigned char* lds, const Params& p) {
;     ...
;                 for (int c = 0; c < 8; ++c) { v[c] = (half ? acc[lc * 2 + lr][c] : acc[lr * 2 + lc][c]) + cbv[c]; s1 += v[c]; s2 += v[c] * v[c]; }
; #pragma unroll
;                 for (int m = 32; m >= 1; m >>= 1) { s1 += __shfl_xor(s1, m); s2 += __shfl_xor(s2, m); }
;                 const float mean = s1 * (1.f / 512.f), var = fmaxf(s2 * (1.f / 512.f) - mean * mean, 0.f), rstd = rsqrtf(var + EPS);
;                 const u32x4 gbr = *(const u32x4*)(GBp + token * 512 + ch0);
;                 const float gbv[8] = {bf_lo(gbr[0]), bf_hi(gbr[0]), bf_lo(gbr[1]), bf_hi(gbr[1]), bf_lo(gbr[2]), bf_hi(gbr[2]), bf_lo(gbr[3]), bf_hi(gbr[3])};
;                 float y[8];
; #pragma unroll
;                 for (int c = 0; c < 8; ++c) { const float t = (v[c] - mean) * rstd * lg[c] + lbv[c]; y[c] = siluf_(t) * gbv[c]; }
;                 u32x4 ob = {cvt_pk_bf16(y[0], y[1]), cvt_pk_bf16(y[2], y[3]), cvt_pk_bf16(y[4], y[5]), cvt_pk_bf16(y[6], y[7])};
;                 *(u32x4*)(A2 + token * 1024 + 512 + ch0) = ob;
;                 const u32x4 fo = *(const u32x4*)(O + token * 512 + ch0), bo = *(const u32x4*)(O + ((size_t)NLAT + token) * 512 + ch0);
;                 float ov[8]; float ss = 0.f;
; #pragma unroll
;                 for (int c = 0; c < 4; ++c) { ov[2 * c] = bf_lo(fo[c]) + bf_lo(bo[c]); ov[2 * c + 1] = bf_hi(fo[c]) + bf_hi(bo[c]); }
; #pragma unroll
;                 for (int c = 0; c < 8; ++c) ss += ov[c] * ov[c];
;                 ss += __shfl_xor(ss, 1); ss += __shfl_xor(ss, 2); ss += __shfl_xor(ss, 4); ss += __shfl_xor(ss, 8);
;                 const float rn = rsqrtf(ss * (1.f / 128.f) + EPS);
;                 const u32x4 gar = *(const u32x4*)(GAp + token * 512 + ch0);
;                 const float gav[8] = {bf_lo(gar[0]), bf_hi(gar[0]), bf_lo(gar[1]), bf_hi(gar[1]), bf_lo(gar[2]), bf_hi(gar[2]), bf_lo(gar[3]), bf_hi(gar[3])};
;                 float z[8];
; #pragma unroll
;                 for (int c = 0; c < 8; ++c) z[c] = ov[c] * rn * hg[c] * gav[c];
;                 u32x4 oa = {cvt_pk_bf16(z[0], z[1]), cvt_pk_bf16(z[2], z[3]), cvt_pk_bf16(z[4], z[5]), cvt_pk_bf16(z[6], z[7])};
;                 *(u32x4*)(A2 + token * 1024 + ch0) = oa;
	v_rcp_f32_e32 v55, v55
	v_rcp_f32_e32 v58, v58
	v_exp_f32_e32 v64, v64
	v_lshlrev_b32_e32 v65, 16, v51
	v_mul_f32_e32 v55, v56, v55
	v_mul_f32_e32 v56, v57, v58
	v_add_f32_e32 v57, 1.0, v64
	v_sub_f32_e32 v58, v61, v59
	v_rcp_f32_e32 v57, v57
	v_mul_f32_e32 v58, v58, v39
	v_fma_f32 v58, v19, v58, v11
	v_mul_f32_e32 v61, 0xbfb8aa3b, v58
	v_and_b32_e32 v51, 0xffff0000, v51
	v_exp_f32_e32 v61, v61
	v_mul_f32_e32 v51, v56, v51
	v_mul_f32_e32 v56, v60, v57
	v_sub_f32_e32 v60, v113, v59
	v_sub_f32_e32 v59, v112, v59
	v_mul_f32_e32 v60, v60, v39
	v_mul_f32_e32 v39, v59, v39
	v_fma_f32 v60, v20, v60, v12
	v_fma_f32 v39, v21, v39, v13
	v_add_f32_e32 v57, 1.0, v61
	v_mul_f32_e32 v61, 0xbfb8aa3b, v60
	v_mul_f32_e32 v59, 0xbfb8aa3b, v39
	v_rcp_f32_e32 v57, v57
	v_exp_f32_e32 v61, v61
	v_exp_f32_e32 v59, v59
	v_mul_f32_e32 v55, v55, v65
	v_mul_f32_e32 v57, v58, v57
	v_add_f32_e32 v58, 1.0, v61
	v_add_f32_e32 v59, 1.0, v59
	v_rcp_f32_e32 v58, v58
	v_rcp_f32_e32 v59, v59
	v_lshlrev_b32_e32 v114, 16, v52
	v_and_b32_e32 v52, 0xffff0000, v52
	v_cvt_pk_bf16_f32 v50, v54, v50
	v_cvt_pk_bf16_f32 v51, v55, v51
	v_lshlrev_b64 v[54:55], 11, v[36:37]
	v_lshlrev_b32_e32 v116, 16, v53
	v_and_b32_e32 v53, 0xffff0000, v53
	v_mul_f32_e32 v52, v57, v52
	v_mul_f32_e32 v57, v60, v58
	v_mul_f32_e32 v39, v39, v59
	v_lshl_add_u64 v[64:65], v[84:85], 0, v[54:55]
	v_mul_f32_e32 v56, v56, v114
	v_mul_f32_e32 v57, v57, v116
	v_mul_f32_e32 v39, v39, v53
	v_cvt_pk_bf16_f32 v52, v56, v52
	v_cvt_pk_bf16_f32 v53, v57, v39
	global_store_dwordx4 v[64:65], v[50:53], off offset:1024
	v_lshl_add_u64 v[58:59], v[72:73], 0, v[62:63]
	s_nop 0
	v_lshl_add_u64 v[50:51], s[68:69], 0, v[62:63]
	v_lshl_add_u64 v[50:51], v[50:51], 0, v[66:67]
	v_add_co_u32_e32 v60, vcc, s35, v50
	s_nop 1
	v_addc_co_u32_e32 v61, vcc, 0, v51, vcc
	s_waitcnt vmcnt(12)
	v_mov_b32_e32 v50, v208
	v_mov_b32_e32 v51, v209
	v_mov_b32_e32 v52, v210
	v_mov_b32_e32 v53, v211
	v_mov_b32_e32 v54, v212
	v_mov_b32_e32 v55, v213
	v_mov_b32_e32 v56, v214
	v_mov_b32_e32 v57, v215
	v_lshl_add_u64 v[58:59], v[74:75], 0, v[62:63]
	s_waitcnt vmcnt(11)
	v_mov_b32_e32 v58, v216
	v_mov_b32_e32 v59, v217
	v_mov_b32_e32 v60, v218
	v_mov_b32_e32 v61, v219
	v_lshlrev_b32_e32 v36, 16, v50
	v_lshlrev_b32_e32 v39, 16, v54
	v_add_f32_e32 v36, v36, v39
	v_and_b32_e32 v39, 0xffff0000, v50
	v_and_b32_e32 v50, 0xffff0000, v54
	v_lshlrev_b32_e32 v63, 16, v51
	v_lshlrev_b32_e32 v113, 16, v55
	v_and_b32_e32 v62, 0xffff0000, v51
	v_and_b32_e32 v112, 0xffff0000, v55
	v_lshlrev_b32_e32 v115, 16, v53
	v_lshlrev_b32_e32 v117, 16, v57
	v_and_b32_e32 v114, 0xffff0000, v53
	v_and_b32_e32 v116, 0xffff0000, v57
	v_add_f32_e32 v39, v39, v50
	v_lshlrev_b32_e32 v51, 16, v52
	v_and_b32_e32 v50, 0xffff0000, v52
	v_pk_add_f32 v[52:53], v[112:113], v[62:63]
	v_pk_add_f32 v[62:63], v[116:117], v[114:115]
	v_mul_f32_e32 v114, v36, v36
	v_lshlrev_b32_e32 v55, 16, v56
	v_and_b32_e32 v54, 0xffff0000, v56
	v_pk_mul_f32 v[56:57], v[52:53], v[52:53]
	v_fmac_f32_e32 v114, v39, v39
	v_pk_add_f32 v[50:51], v[54:55], v[50:51]
	v_add_f32_e32 v57, v57, v114
	v_pk_mul_f32 v[54:55], v[50:51], v[50:51]
	v_add_f32_e32 v56, v56, v57
	v_add_f32_e32 v55, v55, v56
	v_pk_mul_f32 v[112:113], v[62:63], v[62:63]
	v_add_f32_e32 v54, v54, v55
	v_add_f32_e32 v54, v113, v54
	v_add_f32_e32 v54, v112, v54
	s_nop 1
	v_add_f32_dpp v252, v54, v54 quad_perm:[1,0,3,2] row_mask:0xf bank_mask:0xf
	s_nop 1
	v_add_f32_dpp v252, v252, v252 quad_perm:[2,3,0,1] row_mask:0xf bank_mask:0xf
	s_nop 1
	v_add_f32_dpp v252, v252, v252 row_half_mirror row_mask:0xf bank_mask:0xf
	s_nop 1
	v_add_f32_dpp v252, v252, v252 row_mirror row_mask:0xf bank_mask:0xf
	v_and_b32_e32 v56, 0xffff0000, v58
	v_lshlrev_b32_e32 v57, 16, v59
	v_lshlrev_b32_e32 v112, 16, v61
	v_and_b32_e32 v61, 0xffff0000, v61
	v_mov_b32_e32 v54, v252
	v_fmamk_f32 v54, v54, 0x3c000000, v120
	v_mul_f32_e32 v55, 0x4b800000, v54
	v_cmp_gt_f32_e32 vcc, s3, v54
	s_nop 1
	v_cndmask_b32_e32 v54, v54, v55, vcc
	v_rsq_f32_e32 v54, v54
	s_nop 0
	v_mul_f32_e32 v55, 0x45800000, v54
	v_cndmask_b32_e32 v54, v54, v55, vcc
	v_mul_f32_e32 v39, v39, v54
	v_mul_f32_e32 v50, v50, v54
	v_lshlrev_b32_e32 v55, 16, v58
	v_and_b32_e32 v58, 0xffff0000, v59
	v_lshlrev_b32_e32 v59, 16, v60
	v_and_b32_e32 v60, 0xffff0000, v60
	v_mul_f32_e32 v39, v7, v39
	v_mul_f32_e32 v50, v3, v50
	v_mul_f32_e32 v39, v39, v56
	v_mul_f32_e32 v53, v53, v54
	v_mul_f32_e32 v56, v50, v60
	v_mul_f32_e32 v50, v63, v54
	v_mul_f32_e32 v36, v36, v54
	v_mul_f32_e32 v53, v8, v53
	v_mul_f32_e32 v50, v4, v50
	v_mul_f32_e32 v36, v6, v36
	v_mul_f32_e32 v53, v53, v57
	v_mul_f32_e32 v57, v50, v112
	v_mul_f32_e32 v50, v62, v54
	v_mul_f32_e32 v36, v36, v55
	v_mul_f32_e32 v50, v5, v50
	v_mul_f32_e32 v52, v52, v54
	v_mul_f32_e32 v51, v51, v54
	v_mul_f32_e32 v54, v50, v61
	v_cvt_pk_bf16_f32 v50, v36, v39
	v_cndmask_b32_e64 v36, v98, v110, s[6:7]
	v_add_f32_e32 v110, v36, v22
	v_cndmask_b32_e64 v39, v99, v111, s[6:7]
	v_add_f32_e32 v36, 0, v110
	v_add_f32_e32 v111, v39, v23
	v_cndmask_b32_e64 v39, v96, v108, s[6:7]
	v_add_f32_e32 v36, v111, v36
	v_add_f32_e32 v108, v39, v24
	v_mul_f32_e32 v52, v9, v52
	v_mul_f32_e32 v51, v2, v51
	v_add_f32_e32 v39, v108, v36
	v_or_b32_e32 v36, v48, v123
	v_mul_f32_e32 v52, v52, v58
	v_mul_f32_e32 v55, v51, v59
	v_cvt_pk_bf16_f32 v51, v53, v52
	v_lshlrev_b64 v[58:59], 10, v[36:37]
	v_cvt_pk_bf16_f32 v52, v55, v56
	v_cvt_pk_bf16_f32 v53, v57, v54
	global_store_dwordx4 v[64:65], v[50:53], off
	v_mul_f32_e32 v54, v111, v111
	v_fmac_f32_e32 v54, v110, v110
	v_lshl_add_u64 v[50:51], v[70:71], 0, v[58:59]
	s_waitcnt vmcnt(11)
; __device__ __forceinline__ unsigned cvt_pk_bf16(float lo, float hi) { unsigned r; asm volatile("v_cvt_pk_bf16_f32 %0, %1, %2" : "=v"(r) : "v"(lo), "v"(hi)); return r; }
; __device__ __forceinline__ float bf_lo(unsigned u) { return __uint_as_float(u << 16); }
; __device__ __forceinline__ float bf_hi(unsigned u) { return __uint_as_float(u & 0xffff0000u); }
; __device__ __forceinline__ float siluf_(float v) { return v * __builtin_amdgcn_rcpf(1.f + __expf(-v)); }
; __device__ void conv_phase(LAS unsigned char* lds, const Params& p) {
;     ...
;                 const size_t token = (size_t)b * 4096 + (r0 + lr) * 64 + (c0 + lc);
;                 float v[8]; float s1 = 0.f, s2 = 0.f;
; #pragma unroll
;                 for (int c = 0; c < 8; ++c) { v[c] = (half ? acc[lc * 2 + lr][c] : acc[lr * 2 + lc][c]) + cbv[c]; s1 += v[c]; s2 += v[c] * v[c]; }
; #pragma unroll
;                 for (int m = 32; m >= 1; m >>= 1) { s1 += __shfl_xor(s1, m); s2 += __shfl_xor(s2, m); }
;                 const float mean = s1 * (1.f / 512.f), var = fmaxf(s2 * (1.f / 512.f) - mean * mean, 0.f), rstd = rsqrtf(var + EPS);
;                 const u32x4 gbr = *(const u32x4*)(GBp + token * 512 + ch0);
;                 const float gbv[8] = {bf_lo(gbr[0]), bf_hi(gbr[0]), bf_lo(gbr[1]), bf_hi(gbr[1]), bf_lo(gbr[2]), bf_hi(gbr[2]), bf_lo(gbr[3]), bf_hi(gbr[3])};
;                 float y[8];
; #pragma unroll
;                 for (int c = 0; c < 8; ++c) { const float t = (v[c] - mean) * rstd * lg[c] + lbv[c]; y[c] = siluf_(t) * gbv[c]; }
;                 u32x4 ob = {cvt_pk_bf16(y[0], y[1]), cvt_pk_bf16(y[2], y[3]), cvt_pk_bf16(y[4], y[5]), cvt_pk_bf16(y[6], y[7])};
;                 *(u32x4*)(A2 + token * 1024 + 512 + ch0) = ob;
	v_mov_b32_e32 v50, v220
	v_mov_b32_e32 v51, v221
	v_mov_b32_e32 v52, v222
	v_mov_b32_e32 v53, v223
	v_cndmask_b32_e64 v55, v97, v109, s[6:7]
	v_fmac_f32_e32 v54, v108, v108
	v_add_f32_e32 v109, v55, v25
	v_cndmask_b32_e64 v55, v94, v106, s[6:7]
	v_add_f32_e32 v39, v109, v39
	v_fmac_f32_e32 v54, v109, v109
	v_add_f32_e32 v106, v55, v14
	v_cndmask_b32_e64 v55, v95, v107, s[6:7]
	v_pk_add_f32 v[60:61], v[40:41], v[16:17] op_sel:[0,1] op_sel_hi:[1,0]
	v_add_f32_e32 v39, v106, v39
	v_fmac_f32_e32 v54, v106, v106
	v_add_f32_e32 v57, v55, v15
	v_pk_mul_f32 v[62:63], v[60:61], v[60:61]
	v_mov_b32_e32 v56, v40
	v_fmac_f32_e32 v54, v57, v57
	v_pk_add_f32 v[64:65], v[56:57], v[38:39]
	v_pk_mov_b32 v[40:41], v[62:63], v[40:41] op_sel:[1,0]
	v_mov_b32_e32 v55, v17
	v_pk_add_f32 v[40:41], v[40:41], v[54:55]
	v_pk_mul_f32 v[54:55], v[60:61], v[64:65]
	v_pk_add_f32 v[62:63], v[60:61], v[64:65]
	v_pk_add_f32 v[22:23], v[104:105], v[22:23]
	v_mov_b32_e32 v55, v63
	v_pk_add_f32 v[40:41], v[54:55], v[40:41]
	s_nop 1
	v_add_f32_dpp v252, v40, v40 quad_perm:[1,0,3,2] row_mask:0xf bank_mask:0xf
	v_add_f32_dpp v253, v41, v41 quad_perm:[1,0,3,2] row_mask:0xf bank_mask:0xf
	s_nop 0
	v_add_f32_dpp v252, v252, v252 quad_perm:[2,3,0,1] row_mask:0xf bank_mask:0xf
	v_add_f32_dpp v253, v253, v253 quad_perm:[2,3,0,1] row_mask:0xf bank_mask:0xf
	s_nop 0
	v_add_f32_dpp v252, v252, v252 row_half_mirror row_mask:0xf bank_mask:0xf
	v_add_f32_dpp v253, v253, v253 row_half_mirror row_mask:0xf bank_mask:0xf
	s_nop 0
	v_add_f32_dpp v252, v252, v252 row_mirror row_mask:0xf bank_mask:0xf
	v_add_f32_dpp v253, v253, v253 row_mirror row_mask:0xf bank_mask:0xf
	s_nop 0
	v_readlane_b32 s76, v252, 0
	v_readlane_b32 s77, v252, 16
	v_readlane_b32 s78, v252, 32
	v_readlane_b32 s79, v252, 48
	v_readlane_b32 s80, v253, 0
	v_readlane_b32 s81, v253, 16
	v_readlane_b32 s82, v253, 32
	v_readlane_b32 s83, v253, 48
	v_mov_b32_e32 v252, s76
	v_add_f32_e32 v252, s77, v252
	v_add_f32_e32 v252, s78, v252
	v_add_f32_e32 v252, s79, v252
	v_mov_b32_e32 v253, s80
	v_add_f32_e32 v253, s81, v253
	v_add_f32_e32 v253, s82, v253
	v_add_f32_e32 v253, s83, v253
	v_pk_add_f32 v[24:25], v[102:103], v[24:25]
	v_pk_add_f32 v[14:15], v[100:101], v[14:15]
	v_mov_b32_e32 v40, v252
	v_mov_b32_e32 v41, v253
	s_nop 0
	v_pk_mul_f32 v[40:41], v[40:41], s[34:35] op_sel_hi:[1,0]
	v_lshlrev_b32_e32 v54, 16, v51
	v_fma_f32 v39, -v41, v41, v40
	v_max_f32_e32 v39, 0, v39
	v_add_f32_e32 v39, 0x358637bd, v39
	v_mul_f32_e32 v40, 0x4b800000, v39
	v_cmp_gt_f32_e32 vcc, s3, v39
	v_sub_f32_e32 v56, v110, v41
	v_sub_f32_e32 v63, v111, v41
	v_cndmask_b32_e32 v39, v39, v40, vcc
	v_rsq_f32_e32 v39, v39
	v_sub_f32_e32 v106, v106, v41
	v_sub_f32_e32 v57, v57, v41
	v_sub_f32_e32 v61, v61, v41
	v_mul_f32_e32 v40, 0x45800000, v39
	v_cndmask_b32_e32 v39, v39, v40, vcc
	v_mul_f32_e32 v56, v56, v39
	v_fma_f32 v56, v30, v56, v26
	v_mul_f32_e32 v63, v63, v39
	v_mul_f32_e32 v62, 0xbfb8aa3b, v56
	v_fma_f32 v63, v31, v63, v27
	v_exp_f32_e32 v62, v62
	v_mul_f32_e32 v64, 0xbfb8aa3b, v63
	v_exp_f32_e32 v64, v64
	v_lshlrev_b32_e32 v40, 16, v50
	v_add_f32_e32 v62, 1.0, v62
	v_rcp_f32_e32 v62, v62
	v_add_f32_e32 v64, 1.0, v64
	v_rcp_f32_e32 v64, v64
	v_mul_f32_e32 v106, v106, v39
	v_mul_f32_e32 v56, v56, v62
	v_mul_f32_e32 v40, v56, v40
	v_mul_f32_e32 v56, v63, v64
	v_sub_f32_e32 v62, v108, v41
	v_sub_f32_e32 v64, v109, v41
	v_mul_f32_e32 v62, v62, v39
	v_mul_f32_e32 v64, v64, v39
	v_fma_f32 v62, v32, v62, v28
	v_fma_f32 v64, v33, v64, v29
	v_mul_f32_e32 v63, 0xbfb8aa3b, v62
	v_mul_f32_e32 v107, 0xbfb8aa3b, v64
	v_exp_f32_e32 v63, v63
	v_exp_f32_e32 v107, v107
	v_and_b32_e32 v50, 0xffff0000, v50
	v_fma_f32 v106, v18, v106, v10
	v_mul_f32_e32 v50, v56, v50
	v_add_f32_e32 v56, 1.0, v63
	v_add_f32_e32 v63, 1.0, v107
	v_mul_f32_e32 v107, 0xbfb8aa3b, v106
	v_rcp_f32_e32 v56, v56
	v_exp_f32_e32 v107, v107
	v_rcp_f32_e32 v63, v63
	v_mul_f32_e32 v57, v57, v39
	v_mul_f32_e32 v56, v62, v56
	v_add_f32_e32 v62, 1.0, v107
	v_fma_f32 v57, v19, v57, v11
	v_mul_f32_e32 v54, v56, v54
	v_mul_f32_e32 v56, v64, v63
	v_rcp_f32_e32 v62, v62
	v_mul_f32_e32 v63, 0xbfb8aa3b, v57
	v_exp_f32_e32 v63, v63
	v_sub_f32_e32 v41, v60, v41
	v_mul_f32_e32 v61, v61, v39
	v_mul_f32_e32 v39, v41, v39
	v_and_b32_e32 v51, 0xffff0000, v51
	v_fma_f32 v39, v21, v39, v13
	v_lshlrev_b32_e32 v55, 16, v52
	v_mul_f32_e32 v51, v56, v51
	v_mul_f32_e32 v56, v106, v62
	v_fma_f32 v61, v20, v61, v12
	v_mul_f32_e32 v41, 0xbfb8aa3b, v39
	v_mul_f32_e32 v55, v56, v55
	v_add_f32_e32 v56, 1.0, v63
	v_mul_f32_e32 v62, 0xbfb8aa3b, v61
	v_exp_f32_e32 v41, v41
	v_rcp_f32_e32 v56, v56
	v_exp_f32_e32 v62, v62
	v_and_b32_e32 v52, 0xffff0000, v52
	v_add_f32_e32 v41, 1.0, v41
	v_mul_f32_e32 v56, v57, v56
	v_add_f32_e32 v57, 1.0, v62
	v_rcp_f32_e32 v41, v41
	v_rcp_f32_e32 v57, v57
	v_cvt_pk_bf16_f32 v50, v40, v50
	v_lshlrev_b32_e32 v65, 16, v53
	v_mul_f32_e32 v39, v39, v41
	v_lshlrev_b64 v[40:41], 11, v[36:37]
	v_and_b32_e32 v53, 0xffff0000, v53
	v_mul_f32_e32 v52, v56, v52
	v_mul_f32_e32 v56, v61, v57
	v_cvt_pk_bf16_f32 v51, v54, v51
	v_lshl_add_u64 v[40:41], v[84:85], 0, v[40:41]
	v_mul_f32_e32 v56, v56, v65
	v_mul_f32_e32 v39, v39, v53
	v_cvt_pk_bf16_f32 v52, v55, v52
	v_cvt_pk_bf16_f32 v53, v56, v39
	global_store_dwordx4 v[40:41], v[50:53], off offset:1024
	v_lshl_add_u64 v[60:61], v[72:73], 0, v[58:59]
	s_nop 0
	v_lshl_add_u64 v[50:51], s[68:69], 0, v[58:59]
	v_lshl_add_u64 v[50:51], v[50:51], 0, v[66:67]
	v_add_co_u32_e32 v62, vcc, s35, v50
	v_lshl_add_u64 v[58:59], v[74:75], 0, v[58:59]
	s_nop 0
	v_addc_co_u32_e32 v63, vcc, 0, v51, vcc
	s_waitcnt vmcnt(10)
; __device__ __forceinline__ float bf_lo(unsigned u) { return __uint_as_float(u << 16); }
; __device__ void conv_phase(LAS unsigned char* lds, const Params& p) {
;     ...
;                 for (int c = 0; c < 8; ++c) { v[c] = (half ? acc[lc * 2 + lr][c] : acc[lr * 2 + lc][c]) + cbv[c]; s1 += v[c]; s2 += v[c] * v[c]; }
; #pragma unroll
;                 for (int m = 32; m >= 1; m >>= 1) { s1 += __shfl_xor(s1, m); s2 += __shfl_xor(s2, m); }
;                 const float mean = s1 * (1.f / 512.f), var = fmaxf(s2 * (1.f / 512.f) - mean * mean, 0.f), rstd = rsqrtf(var + EPS);
;                 const u32x4 gbr = *(const u32x4*)(GBp + token * 512 + ch0);
;                 const float gbv[8] = {bf_lo(gbr[0]), bf_hi(gbr[0]), bf_lo(gbr[1]), bf_hi(gbr[1]), bf_lo(gbr[2]), bf_hi(gbr[2]), bf_lo(gbr[3]), bf_hi(gbr[3])};
;                 float y[8];
; #pragma unroll
;                 for (int c = 0; c < 8; ++c) { const float t = (v[c] - mean) * rstd * lg[c] + lbv[c]; y[c] = siluf_(t) * gbv[c]; }
;                 u32x4 ob = {cvt_pk_bf16(y[0], y[1]), cvt_pk_bf16(y[2], y[3]), cvt_pk_bf16(y[4], y[5]), cvt_pk_bf16(y[6], y[7])};
;                 *(u32x4*)(A2 + token * 1024 + 512 + ch0) = ob;
;                 const u32x4 fo = *(const u32x4*)(O + token * 512 + ch0), bo = *(const u32x4*)(O + ((size_t)NLAT + token) * 512 + ch0);
;                 float ov[8]; float ss = 0.f;
; #pragma unroll
;                 for (int c = 0; c < 4; ++c) { ov[2 * c] = bf_lo(fo[c]) + bf_lo(bo[c]); ov[2 * c + 1] = bf_hi(fo[c]) + bf_hi(bo[c]); }
; #pragma unroll
;                 for (int c = 0; c < 8; ++c) ss += ov[c] * ov[c];
;                 ss += __shfl_xor(ss, 1); ss += __shfl_xor(ss, 2); ss += __shfl_xor(ss, 4); ss += __shfl_xor(ss, 8);
;                 const float rn = rsqrtf(ss * (1.f / 128.f) + EPS);
;                 const u32x4 gar = *(const u32x4*)(GAp + token * 512 + ch0);
;                 const float gav[8] = {bf_lo(gar[0]), bf_hi(gar[0]), bf_lo(gar[1]), bf_hi(gar[1]), bf_lo(gar[2]), bf_hi(gar[2]), bf_lo(gar[3]), bf_hi(gar[3])};
;                 float z[8];
; #pragma unroll
;                 for (int c = 0; c < 8; ++c) z[c] = ov[c] * rn * hg[c] * gav[c];
;                 u32x4 oa = {cvt_pk_bf16(z[0], z[1]), cvt_pk_bf16(z[2], z[3]), cvt_pk_bf16(z[4], z[5]), cvt_pk_bf16(z[6], z[7])};
;                 *(u32x4*)(A2 + token * 1024 + ch0) = oa;
	v_mov_b32_e32 v50, v224
	v_mov_b32_e32 v51, v225
	v_mov_b32_e32 v52, v226
	v_mov_b32_e32 v53, v227
	v_mov_b32_e32 v54, v228
	v_mov_b32_e32 v55, v229
	v_mov_b32_e32 v56, v230
	v_mov_b32_e32 v57, v231
	v_lshlrev_b32_e32 v36, 16, v50
	s_waitcnt vmcnt(9)
	v_mov_b32_e32 v58, v232
	v_mov_b32_e32 v59, v233
	v_mov_b32_e32 v60, v234
	v_mov_b32_e32 v61, v235
	v_lshlrev_b32_e32 v39, 16, v54
	v_add_f32_e32 v36, v36, v39
	v_and_b32_e32 v39, 0xffff0000, v50
	v_and_b32_e32 v50, 0xffff0000, v54
	v_lshlrev_b32_e32 v63, 16, v51
	v_lshlrev_b32_e32 v65, 16, v55
	v_and_b32_e32 v62, 0xffff0000, v51
	v_and_b32_e32 v64, 0xffff0000, v55
	v_lshlrev_b32_e32 v107, 16, v53
	v_lshlrev_b32_e32 v109, 16, v57
	v_and_b32_e32 v106, 0xffff0000, v53
	v_and_b32_e32 v108, 0xffff0000, v57
	v_add_f32_e32 v39, v39, v50
	v_lshlrev_b32_e32 v51, 16, v52
	v_and_b32_e32 v50, 0xffff0000, v52
	v_pk_add_f32 v[52:53], v[64:65], v[62:63]
	v_pk_add_f32 v[62:63], v[108:109], v[106:107]
	v_mul_f32_e32 v106, v36, v36
	v_lshlrev_b32_e32 v55, 16, v56
	v_and_b32_e32 v54, 0xffff0000, v56
	v_pk_mul_f32 v[56:57], v[52:53], v[52:53]
	v_fmac_f32_e32 v106, v39, v39
	v_pk_add_f32 v[50:51], v[54:55], v[50:51]
	v_add_f32_e32 v57, v57, v106
	v_pk_mul_f32 v[54:55], v[50:51], v[50:51]
	v_add_f32_e32 v56, v56, v57
	v_add_f32_e32 v55, v55, v56
	v_pk_mul_f32 v[64:65], v[62:63], v[62:63]
	v_add_f32_e32 v54, v54, v55
	v_add_f32_e32 v54, v65, v54
	v_add_f32_e32 v54, v64, v54
	s_nop 1
	v_add_f32_dpp v252, v54, v54 quad_perm:[1,0,3,2] row_mask:0xf bank_mask:0xf
	s_nop 1
	v_add_f32_dpp v252, v252, v252 quad_perm:[2,3,0,1] row_mask:0xf bank_mask:0xf
	s_nop 1
	v_add_f32_dpp v252, v252, v252 row_half_mirror row_mask:0xf bank_mask:0xf
	s_nop 1
	v_add_f32_dpp v252, v252, v252 row_mirror row_mask:0xf bank_mask:0xf
	v_mov_b32_e32 v54, v252
	v_fmamk_f32 v54, v54, 0x3c000000, v120
	v_mul_f32_e32 v55, 0x4b800000, v54
	v_cmp_gt_f32_e32 vcc, s3, v54
	v_and_b32_e32 v56, 0xffff0000, v58
	v_cndmask_b32_e32 v54, v54, v55, vcc
	v_rsq_f32_e32 v54, v54
	v_lshlrev_b32_e32 v57, 16, v59
	v_lshlrev_b32_e32 v64, 16, v61
	v_and_b32_e32 v61, 0xffff0000, v61
	v_mul_f32_e32 v55, 0x45800000, v54
	v_cndmask_b32_e32 v54, v54, v55, vcc
	v_mul_f32_e32 v39, v39, v54
	v_mul_f32_e32 v50, v50, v54
	v_lshlrev_b32_e32 v55, 16, v58
	v_and_b32_e32 v58, 0xffff0000, v59
	v_lshlrev_b32_e32 v59, 16, v60
	v_and_b32_e32 v60, 0xffff0000, v60
	v_mul_f32_e32 v39, v7, v39
	v_mul_f32_e32 v50, v3, v50
	v_mul_f32_e32 v39, v39, v56
	v_mul_f32_e32 v53, v53, v54
	v_mul_f32_e32 v56, v50, v60
	v_mul_f32_e32 v50, v63, v54
	v_mul_f32_e32 v36, v36, v54
	v_mul_f32_e32 v53, v8, v53
	v_mul_f32_e32 v50, v4, v50
	v_mul_f32_e32 v36, v6, v36
	v_mul_f32_e32 v53, v53, v57
	v_mul_f32_e32 v52, v52, v54
	v_mul_f32_e32 v57, v50, v64
	v_mul_f32_e32 v50, v62, v54
	v_mul_f32_e32 v36, v36, v55
	v_mul_f32_e32 v52, v9, v52
	v_mul_f32_e32 v51, v51, v54
	v_mul_f32_e32 v50, v5, v50
	v_mul_f32_e32 v52, v52, v58
	v_mul_f32_e32 v51, v2, v51
	v_mul_f32_e32 v54, v50, v61
	v_cvt_pk_bf16_f32 v50, v36, v39
	v_add_f32_e32 v36, 0, v22
	v_mul_f32_e32 v55, v51, v59
	v_cvt_pk_bf16_f32 v51, v53, v52
	v_cvt_pk_bf16_f32 v52, v55, v56
	v_cvt_pk_bf16_f32 v53, v57, v54
	v_add_f32_e32 v39, v23, v36
	v_or_b32_e32 v36, v48, v49
	global_store_dwordx4 v[40:41], v[50:53], off
	v_mul_f32_e32 v40, v23, v23
	v_pk_fma_f32 v[40:41], v[22:23], v[22:23], v[40:41] op_sel_hi:[1,1,0]
	v_lshlrev_b64 v[52:53], 10, v[36:37]
	v_lshl_add_u64 v[48:49], v[70:71], 0, v[52:53]
	s_waitcnt vmcnt(9)
	v_mov_b32_e32 v48, v236
	v_mov_b32_e32 v49, v237
	v_mov_b32_e32 v50, v238
	v_mov_b32_e32 v51, v239
	v_pk_fma_f32 v[40:41], v[24:25], v[24:25], v[40:41]
	v_mul_f32_e32 v54, v25, v25
	v_pk_add_f32 v[40:41], v[54:55], v[40:41] op_sel_hi:[0,1]
	v_add_f32_e32 v39, v24, v39
	v_pk_fma_f32 v[40:41], v[14:15], v[14:15], v[40:41]
	v_mul_f32_e32 v54, v15, v15
	v_add_f32_e32 v39, v25, v39
	v_pk_add_f32 v[40:41], v[54:55], v[40:41] op_sel_hi:[0,1]
	v_pk_add_f32 v[54:55], v[34:35], v[16:17] op_sel:[0,1] op_sel_hi:[1,0]
	v_add_f32_e32 v39, v14, v39
	v_pk_mul_f32 v[56:57], v[54:55], v[54:55]
	v_mov_b32_e32 v58, v34
	v_mov_b32_e32 v59, v15
	v_pk_add_f32 v[38:39], v[58:59], v[38:39]
	v_pk_mov_b32 v[34:35], v[56:57], v[34:35] op_sel:[1,0]
	v_mov_b32_e32 v41, v17
	v_pk_add_f32 v[16:17], v[34:35], v[40:41]
	v_pk_mul_f32 v[34:35], v[54:55], v[38:39]
	v_pk_add_f32 v[38:39], v[54:55], v[38:39]
	v_lshlrev_b32_e32 v40, 16, v50
	v_mov_b32_e32 v35, v39
	v_pk_add_f32 v[16:17], v[34:35], v[16:17]
	s_nop 1
	v_add_f32_dpp v252, v16, v16 quad_perm:[1,0,3,2] row_mask:0xf bank_mask:0xf
	v_add_f32_dpp v253, v17, v17 quad_perm:[1,0,3,2] row_mask:0xf bank_mask:0xf
	s_nop 0
	v_add_f32_dpp v252, v252, v252 quad_perm:[2,3,0,1] row_mask:0xf bank_mask:0xf
	v_add_f32_dpp v253, v253, v253 quad_perm:[2,3,0,1] row_mask:0xf bank_mask:0xf
	s_nop 0
	v_add_f32_dpp v252, v252, v252 row_half_mirror row_mask:0xf bank_mask:0xf
	v_add_f32_dpp v253, v253, v253 row_half_mirror row_mask:0xf bank_mask:0xf
	s_nop 0
	v_add_f32_dpp v252, v252, v252 row_mirror row_mask:0xf bank_mask:0xf
	v_add_f32_dpp v253, v253, v253 row_mirror row_mask:0xf bank_mask:0xf
	s_nop 0
	v_readlane_b32 s76, v252, 0
	v_readlane_b32 s77, v252, 16
	v_readlane_b32 s78, v252, 32
	v_readlane_b32 s79, v252, 48
	v_readlane_b32 s80, v253, 0
	v_readlane_b32 s81, v253, 16
	v_readlane_b32 s82, v253, 32
	v_readlane_b32 s83, v253, 48
	v_mov_b32_e32 v252, s76
	v_add_f32_e32 v252, s77, v252
	v_add_f32_e32 v252, s78, v252
	v_add_f32_e32 v252, s79, v252
	v_mov_b32_e32 v253, s80
	v_add_f32_e32 v253, s81, v253
	v_add_f32_e32 v253, s82, v253
	v_add_f32_e32 v253, s83, v253
	v_and_b32_e32 v41, 0xffff0000, v50
	v_lshlrev_b32_e32 v38, 16, v49
; __device__ void conv_phase(LAS unsigned char* lds, const Params& p) {
;     ...
;     for (int it = blockIdx.x * 8 + w; it < 8192; it += gridDim.x * 8) {
;     ...
;                 for (int c = 0; c < 8; ++c) { v[c] = (half ? acc[lc * 2 + lr][c] : acc[lr * 2 + lc][c]) + cbv[c]; s1 += v[c]; s2 += v[c] * v[c]; }
; #pragma unroll
;                 for (int m = 32; m >= 1; m >>= 1) { s1 += __shfl_xor(s1, m); s2 += __shfl_xor(s2, m); }
;                 const float mean = s1 * (1.f / 512.f), var = fmaxf(s2 * (1.f / 512.f) - mean * mean, 0.f), rstd = rsqrtf(var + EPS);
;                 const u32x4 gbr = *(const u32x4*)(GBp + token * 512 + ch0);
;                 const float gbv[8] = {bf_lo(gbr[0]), bf_hi(gbr[0]), bf_lo(gbr[1]), bf_hi(gbr[1]), bf_lo(gbr[2]), bf_hi(gbr[2]), bf_lo(gbr[3]), bf_hi(gbr[3])};
;                 float y[8];
; #pragma unroll
;                 for (int c = 0; c < 8; ++c) { const float t = (v[c] - mean) * rstd * lg[c] + lbv[c]; y[c] = siluf_(t) * gbv[c]; }
;                 u32x4 ob = {cvt_pk_bf16(y[0], y[1]), cvt_pk_bf16(y[2], y[3]), cvt_pk_bf16(y[4], y[5]), cvt_pk_bf16(y[6], y[7])};
;                 *(u32x4*)(A2 + token * 1024 + 512 + ch0) = ob;
;                 const u32x4 fo = *(const u32x4*)(O + token * 512 + ch0), bo = *(const u32x4*)(O + ((size_t)NLAT + token) * 512 + ch0);
;                 float ov[8]; float ss = 0.f;
; #pragma unroll
;                 for (int c = 0; c < 4; ++c) { ov[2 * c] = bf_lo(fo[c]) + bf_lo(bo[c]); ov[2 * c + 1] = bf_hi(fo[c]) + bf_hi(bo[c]); }
; #pragma unroll
;                 for (int c = 0; c < 8; ++c) ss += ov[c] * ov[c];
;                 ss += __shfl_xor(ss, 1); ss += __shfl_xor(ss, 2); ss += __shfl_xor(ss, 4); ss += __shfl_xor(ss, 8);
;                 const float rn = rsqrtf(ss * (1.f / 128.f) + EPS);
;                 const u32x4 gar = *(const u32x4*)(GAp + token * 512 + ch0);
;                 const float gav[8] = {bf_lo(gar[0]), bf_hi(gar[0]), bf_lo(gar[1]), bf_hi(gar[1]), bf_lo(gar[2]), bf_hi(gar[2]), bf_lo(gar[3]), bf_hi(gar[3])};
;                 float z[8];
; #pragma unroll
;                 for (int c = 0; c < 8; ++c) z[c] = ov[c] * rn * hg[c] * gav[c];
;                 u32x4 oa = {cvt_pk_bf16(z[0], z[1]), cvt_pk_bf16(z[2], z[3]), cvt_pk_bf16(z[4], z[5]), cvt_pk_bf16(z[6], z[7])};
;                 *(u32x4*)(A2 + token * 1024 + ch0) = oa;
;             }
;     }
	v_and_b32_e32 v39, 0xffff0000, v49
	v_mov_b32_e32 v16, v252
	v_mov_b32_e32 v17, v253
	s_nop 0
	v_pk_mul_f32 v[16:17], v[16:17], s[34:35] op_sel_hi:[1,0]
	v_and_b32_e32 v35, 0xffff0000, v48
	v_fma_f32 v16, -v17, v17, v16
	v_max_f32_e32 v16, 0, v16
	v_add_f32_e32 v16, 0x358637bd, v16
	v_mul_f32_e32 v34, 0x4b800000, v16
	v_cmp_gt_f32_e32 vcc, s3, v16
	v_sub_f32_e32 v14, v14, v17
	v_sub_f32_e32 v22, v22, v17
	v_cndmask_b32_e32 v16, v16, v34, vcc
	v_rsq_f32_e32 v16, v16
	v_sub_f32_e32 v15, v15, v17
	v_sub_f32_e32 v23, v23, v17
	v_sub_f32_e32 v24, v24, v17
	v_mul_f32_e32 v34, 0x45800000, v16
	v_cndmask_b32_e32 v16, v16, v34, vcc
	v_mul_f32_e32 v14, v14, v16
	v_fma_f32 v10, v18, v14, v10
	v_mul_f32_e32 v14, 0xbfb8aa3b, v10
	v_exp_f32_e32 v14, v14
	v_mul_f32_e32 v22, v22, v16
	v_fma_f32 v22, v30, v22, v26
	v_mul_f32_e32 v15, v15, v16
	v_mul_f32_e32 v26, 0xbfb8aa3b, v22
	v_add_f32_e32 v14, 1.0, v14
	v_fma_f32 v11, v19, v15, v11
	v_exp_f32_e32 v26, v26
	v_rcp_f32_e32 v14, v14
	v_mul_f32_e32 v15, 0xbfb8aa3b, v11
	v_exp_f32_e32 v15, v15
	v_add_f32_e32 v26, 1.0, v26
	v_mul_f32_e32 v10, v10, v14
	v_rcp_f32_e32 v26, v26
	v_mul_f32_e32 v14, v10, v40
	v_add_f32_e32 v10, 1.0, v15
	v_sub_f32_e32 v15, v55, v17
	v_sub_f32_e32 v25, v25, v17
	v_mul_f32_e32 v15, v15, v16
	v_sub_f32_e32 v17, v54, v17
	v_mul_f32_e32 v23, v23, v16
	v_mul_f32_e32 v24, v24, v16
	v_mul_f32_e32 v25, v25, v16
	v_fma_f32 v12, v20, v15, v12
	v_mul_f32_e32 v16, v17, v16
	v_fma_f32 v23, v31, v23, v27
	v_fma_f32 v24, v32, v24, v28
	v_fmac_f32_e32 v29, v33, v25
	v_mul_f32_e32 v15, 0xbfb8aa3b, v12
	v_fmac_f32_e32 v13, v21, v16
	v_mul_f32_e32 v27, 0xbfb8aa3b, v23
	v_mul_f32_e32 v22, v22, v26
	v_mul_f32_e32 v26, 0xbfb8aa3b, v24
	v_mul_f32_e32 v25, 0xbfb8aa3b, v29
	v_rcp_f32_e32 v10, v10
	v_exp_f32_e32 v15, v15
	v_mul_f32_e32 v16, 0xbfb8aa3b, v13
	v_exp_f32_e32 v27, v27
	v_exp_f32_e32 v26, v26
	v_exp_f32_e32 v25, v25
	v_exp_f32_e32 v16, v16
	v_mul_f32_e32 v10, v11, v10
	v_add_f32_e32 v11, 1.0, v15
	v_add_f32_e32 v27, 1.0, v27
	v_add_f32_e32 v26, 1.0, v26
	v_add_f32_e32 v25, 1.0, v25
	v_rcp_f32_e32 v11, v11
	v_add_f32_e32 v15, 1.0, v16
	v_rcp_f32_e32 v27, v27
	v_rcp_f32_e32 v26, v26
	v_rcp_f32_e32 v25, v25
	v_rcp_f32_e32 v15, v15
	v_lshlrev_b32_e32 v30, 16, v51
	v_mul_f32_e32 v16, v10, v41
	v_mul_f32_e32 v10, v12, v11
	v_lshlrev_b32_e32 v34, 16, v48
	v_and_b32_e32 v31, 0xffff0000, v51
	v_mul_f32_e32 v23, v23, v27
	v_mul_f32_e32 v18, v24, v26
	v_mul_f32_e32 v24, v29, v25
	v_mul_f32_e32 v17, v10, v30
	v_mul_f32_e32 v10, v13, v15
	v_mul_f32_e32 v22, v22, v34
	v_mul_f32_e32 v23, v23, v35
	v_mul_f32_e32 v18, v18, v38
	v_mul_f32_e32 v19, v24, v39
	v_mul_f32_e32 v13, v10, v31
	v_cvt_pk_bf16_f32 v10, v22, v23
	v_cvt_pk_bf16_f32 v11, v18, v19
	v_cvt_pk_bf16_f32 v12, v14, v16
	v_lshlrev_b64 v[14:15], 11, v[36:37]
	v_lshl_add_u64 v[22:23], v[84:85], 0, v[14:15]
	v_cvt_pk_bf16_f32 v13, v17, v13
	global_store_dwordx4 v[22:23], v[10:13], off offset:1024
	v_lshl_add_u64 v[18:19], v[72:73], 0, v[52:53]
	s_nop 0
	v_lshl_add_u64 v[10:11], s[68:69], 0, v[52:53]
	v_lshl_add_u64 v[10:11], v[10:11], 0, v[66:67]
	v_add_co_u32_e32 v20, vcc, s35, v10
	s_nop 1
	v_addc_co_u32_e32 v21, vcc, 0, v11, vcc
	s_waitcnt vmcnt(8)
	v_mov_b32_e32 v10, v240
	v_mov_b32_e32 v11, v241
	v_mov_b32_e32 v12, v242
	v_mov_b32_e32 v13, v243
	v_mov_b32_e32 v14, v244
	v_mov_b32_e32 v15, v245
	v_mov_b32_e32 v16, v246
	v_mov_b32_e32 v17, v247
	v_lshl_add_u64 v[18:19], v[74:75], 0, v[52:53]
	s_waitcnt vmcnt(7)
	v_mov_b32_e32 v18, v248
	v_mov_b32_e32 v19, v249
	v_mov_b32_e32 v20, v250
	v_mov_b32_e32 v21, v251
	v_lshlrev_b32_e32 v24, 16, v10
	v_lshlrev_b32_e32 v25, 16, v14
	v_add_f32_e32 v32, v24, v25
	v_and_b32_e32 v10, 0xffff0000, v10
	v_and_b32_e32 v14, 0xffff0000, v14
	v_lshlrev_b32_e32 v25, 16, v11
	v_lshlrev_b32_e32 v27, 16, v15
	v_and_b32_e32 v24, 0xffff0000, v11
	v_and_b32_e32 v26, 0xffff0000, v15
	v_lshlrev_b32_e32 v29, 16, v13
	v_lshlrev_b32_e32 v31, 16, v17
	v_and_b32_e32 v28, 0xffff0000, v13
	v_and_b32_e32 v30, 0xffff0000, v17
	v_add_f32_e32 v33, v10, v14
	v_lshlrev_b32_e32 v11, 16, v12
	v_and_b32_e32 v10, 0xffff0000, v12
	v_pk_add_f32 v[12:13], v[26:27], v[24:25]
	v_pk_add_f32 v[24:25], v[30:31], v[28:29]
	v_mul_f32_e32 v28, v32, v32
	v_lshlrev_b32_e32 v15, 16, v16
	v_and_b32_e32 v14, 0xffff0000, v16
	v_pk_mul_f32 v[16:17], v[12:13], v[12:13]
	v_fmac_f32_e32 v28, v33, v33
	v_pk_add_f32 v[10:11], v[14:15], v[10:11]
	v_add_f32_e32 v17, v17, v28
	v_pk_mul_f32 v[14:15], v[10:11], v[10:11]
	v_add_f32_e32 v16, v16, v17
	v_add_f32_e32 v15, v15, v16
	v_pk_mul_f32 v[26:27], v[24:25], v[24:25]
	v_add_f32_e32 v14, v14, v15
	v_add_f32_e32 v14, v27, v14
	v_add_f32_e32 v14, v26, v14
	s_nop 1
	v_add_f32_dpp v252, v14, v14 quad_perm:[1,0,3,2] row_mask:0xf bank_mask:0xf
	s_nop 1
	v_add_f32_dpp v252, v252, v252 quad_perm:[2,3,0,1] row_mask:0xf bank_mask:0xf
	s_nop 1
	v_add_f32_dpp v252, v252, v252 row_half_mirror row_mask:0xf bank_mask:0xf
	s_nop 1
	v_add_f32_dpp v252, v252, v252 row_mirror row_mask:0xf bank_mask:0xf
	v_and_b32_e32 v16, 0xffff0000, v18
	v_lshlrev_b32_e32 v17, 16, v19
	v_lshlrev_b32_e32 v26, 16, v21
	v_and_b32_e32 v21, 0xffff0000, v21
	v_mov_b32_e32 v14, v252
	v_fmamk_f32 v14, v14, 0x3c000000, v120
	v_mul_f32_e32 v15, 0x4b800000, v14
	v_cmp_gt_f32_e32 vcc, s3, v14
	s_nop 1
	v_cndmask_b32_e32 v14, v14, v15, vcc
	v_rsq_f32_e32 v14, v14
	s_nop 0
	v_mul_f32_e32 v15, 0x45800000, v14
	v_cndmask_b32_e32 v14, v14, v15, vcc
	v_mul_f32_e32 v11, v11, v14
	v_lshlrev_b32_e32 v15, 16, v18
	v_and_b32_e32 v18, 0xffff0000, v19
	v_lshlrev_b32_e32 v19, 16, v20
	v_mul_f32_e32 v2, v2, v11
	v_mul_f32_e32 v11, v2, v19
	v_mul_f32_e32 v2, v10, v14
	v_and_b32_e32 v20, 0xffff0000, v20
	v_mul_f32_e32 v2, v3, v2
	v_mul_f32_e32 v10, v2, v20
	v_mul_f32_e32 v2, v25, v14
	v_mul_f32_e32 v27, v32, v14
	v_mul_f32_e32 v12, v12, v14
	v_mul_f32_e32 v2, v4, v2
	v_mul_f32_e32 v6, v6, v27
	v_mul_f32_e32 v9, v9, v12
	v_mul_f32_e32 v12, v2, v26
	v_mul_f32_e32 v2, v24, v14
	v_mul_f32_e32 v6, v6, v15
	v_mul_f32_e32 v15, v33, v14
	v_mul_f32_e32 v13, v13, v14
	v_mul_f32_e32 v2, v5, v2
	v_mul_f32_e32 v7, v7, v15
	v_mul_f32_e32 v8, v8, v13
	v_mul_f32_e32 v5, v2, v21
	v_mul_f32_e32 v7, v7, v16
	v_mul_f32_e32 v8, v8, v17
	v_mul_f32_e32 v9, v9, v18
	v_cvt_pk_bf16_f32 v2, v6, v7
	v_cvt_pk_bf16_f32 v3, v8, v9
	v_cvt_pk_bf16_f32 v4, v11, v10
	v_cvt_pk_bf16_f32 v5, v12, v5
	global_store_dwordx4 v[22:23], v[2:5], off
	s_load_dword s4, s[28:29], 0x0
	s_waitcnt lgkmcnt(0)
	v_lshl_add_u32 v1, s4, 3, v1
	v_cmp_lt_i32_e32 vcc, s40, v1
	s_or_b64 s[30:31], vcc, s[30:31]
	s_andn2_b64 exec, exec, s[30:31]
	s_cbranch_execz .LBB0_377
